# GEMM K-loop: scalar address arithmetic that trailed three MFMA blocks (before their closing barrier) interleaved into the MFMA issue shadow
# speedup vs baseline: 1.0199x; 1.0167x over previous
; #define LDA(dst, b, h) for (int m = 0; m < 4; ++m) for (int k = 0; k < 2; ++k) \
;     dst[m][k] = *reinterpret_cast<const bf16x8*>(SA(b, h) + lds_byte(wr * 64 + m * 16 + fr, k * 32 + fq * 8))
; #define LDB(dst, b, h) for (int n = 0; n < 2; ++n) for (int k = 0; k < 2; ++k) \
;     dst[n][k] = *reinterpret_cast<const bf16x8*>(SB(b, h) + lds_byte(wc * 32 + n * 16 + fr, k * 32 + fq * 8))
; #define MMA(ai, bj, At_, Bt_) do { __builtin_amdgcn_s_setprio(1); \
;     for (int m = 0; m < 4; ++m) for (int n = 0; n < 2; ++n) for (int k = 0; k < 2; ++k) \
;       acc[ai][bj][m][n] = __builtin_amdgcn_mfma_f32_16x16x32_bf16(Bt_[n][k], At_[m][k], acc[ai][bj][m][n], 0, 0, 0); \
;     __builtin_amdgcn_s_setprio(0); } while (0)
; #define WAIT_V(n) asm volatile("s_waitcnt vmcnt(" #n ")" ::: "memory")
; #define WAIT_L(n) asm volatile("s_waitcnt lgkmcnt(" #n ")" ::: "memory")
; #define BAR __builtin_amdgcn_s_barrier()
; #define SCHED __builtin_amdgcn_sched_barrier(0)
; #define STG(P, PTR, LD, O0) do { const bf16_t* _g = (PTR); \
;     __builtin_amdgcn_global_load_lds((const unsigned*)(_g + O0), (lds_u32*)((P) + swave * 1024), 16, 0, 0); \
;     __builtin_amdgcn_global_load_lds((const unsigned*)(_g + (size_t)64 * (LD) + O0), (lds_u32*)((P) + swave * 1024 + 8192), 16, 0, 0); } while (0)
; #define LDA(dst, b, h) for (int m = 0; m < 4; ++m) for (int k = 0; k < 2; ++k) \
;     dst[m][k] = *reinterpret_cast<const bf16x8*>(SA(b, h) + lds_byte(wr * 64 + m * 16 + fr, k * 32 + fq * 8))
; #define LDB(dst, b, h) for (int n = 0; n < 2; ++n) for (int k = 0; k < 2; ++k) \
;     dst[n][k] = *reinterpret_cast<const bf16x8*>(SB(b, h) + lds_byte(wc * 32 + n * 16 + fr, k * 32 + fq * 8))
; #define WAIT_V(n) asm volatile("s_waitcnt vmcnt(" #n ")" ::: "memory")
; #define WAIT_L(n) asm volatile("s_waitcnt lgkmcnt(" #n ")" ::: "memory")
; __device__ __forceinline__ void gemm_stream(int swave, const GemmJob& J, char* shm, int vb, int G) {
;     ...
;       LDB(B0, 0, 0); SCHED; LDA(At, 0, 0); STGA(SA(1, 1), cA, cA1, t + 1, 1);
;       WAIT_L(8); BAR; WAIT_L(0); MMA(0, 0, At, B0); BAR; SCHED;
;       LDB(B1, 0, 1); STG(SB(0, 0), b2, ldb, offB0);
;       BAR; WAIT_L(0); MMA(0, 1, At, B1); BAR;
;       LDA(At, 0, 1); STGA(SA(0, 0), xA, xA1, k2, 0);
;       BAR; WAIT_L(0); MMA(1, 0, At, B0); BAR; SCHED;
;       STG(SB(0, 1), b2 + hB, ldb, offB0);
;       WAIT_V(6); BAR; MMA(1, 1, At, B1); BAR;
.LBB0_729:
	ds_read_b128 v[164:167], v139
	ds_read_b128 v[168:171], v139 offset:1024
	ds_read_b128 v[172:175], v139 offset:2048
	ds_read_b128 v[176:179], v139 offset:3072
	s_cmp_eq_u32 s49, s29
	s_cselect_b64 s[68:69], -1, 0
	s_and_b64 s[64:65], s[68:69], exec
	s_cselect_b32 s52, s10, s8
	s_cselect_b32 s64, s11, s9
	s_add_i32 s33, s2, 2
	s_and_b64 s[68:69], s[68:69], exec
	s_cselect_b32 s71, s15, s21
	s_cselect_b32 s70, s14, s20
	s_cselect_b32 s68, 0, s33
	s_cselect_b32 s65, s12, s16
	s_cselect_b32 s66, s13, s17
	s_or_b32 s2, s2, 1
	s_cmp_lt_u32 s2, s36
	s_cselect_b64 vcc, -1, 0
	s_and_b64 s[2:3], vcc, exec
	s_cselect_b32 s3, 0, s36
	s_cselect_b32 s2, s38, s37
	s_not_b32 s3, s3
	s_add_i32 s94, s3, s29
	s_and_b64 s[72:73], vcc, exec
	s_cselect_b32 s3, s9, s17
	s_cselect_b32 s69, s8, s16
	s_lshl_b64 s[72:73], s[94:95], 7
	s_add_u32 s69, s69, s72
	s_addc_u32 s74, s3, s73
	s_mov_b32 s3, s95
	s_lshl_b64 s[72:73], s[2:3], 8
	s_add_u32 s72, s69, s72
	v_cndmask_b32_e32 v2, v138, v0, vcc
	s_addc_u32 s73, s74, s73
	s_add_i32 m0, s42, 0xc000
	s_lshl_b64 s[2:3], s[2:3], 7
	v_lshlrev_b64 v[212:213], 1, v[2:3]
	s_add_u32 s2, s72, s2
	v_lshl_add_u64 v[214:215], s[72:73], 0, v[212:213]
	s_addc_u32 s3, s73, s3
	ds_read_b128 v[180:183], v144
	ds_read_b128 v[184:187], v144 offset:1024
	ds_read_b128 v[188:191], v145
	ds_read_b128 v[192:195], v145 offset:1024
	ds_read_b128 v[196:199], v159
	ds_read_b128 v[200:203], v159 offset:1024
	ds_read_b128 v[204:207], v160
	ds_read_b128 v[208:211], v160 offset:1024
	global_load_lds_dwordx4 v[214:215], off
	v_lshl_add_u64 v[212:213], s[2:3], 0, v[212:213]
	s_add_i32 m0, s42, 0xe000
	s_nop 0
	global_load_lds_dwordx4 v[212:213], off
	s_waitcnt lgkmcnt(8)
	s_barrier
	s_waitcnt lgkmcnt(0)
	s_waitcnt lgkmcnt(0)
	v_mfma_f32_16x16x32_bf16 v[128:131], v[164:167], v[180:183], v[128:131]
	v_mfma_f32_16x16x32_bf16 v[124:127], v[172:175], v[180:183], v[124:127]
	v_mfma_f32_16x16x32_bf16 v[120:123], v[164:167], v[188:191], v[120:123]
	v_mfma_f32_16x16x32_bf16 v[116:119], v[172:175], v[188:191], v[116:119]
	v_mfma_f32_16x16x32_bf16 v[104:107], v[164:167], v[196:199], v[104:107]
	v_mfma_f32_16x16x32_bf16 v[100:103], v[172:175], v[196:199], v[100:103]
	v_mfma_f32_16x16x32_bf16 v[88:91], v[164:167], v[204:207], v[88:91]
	v_mfma_f32_16x16x32_bf16 v[84:87], v[172:175], v[204:207], v[84:87]
	v_mfma_f32_16x16x32_bf16 v[128:131], v[168:171], v[184:187], v[128:131]
	v_mfma_f32_16x16x32_bf16 v[124:127], v[176:179], v[184:187], v[124:127]
	v_mfma_f32_16x16x32_bf16 v[120:123], v[168:171], v[192:195], v[120:123]
	v_mfma_f32_16x16x32_bf16 v[116:119], v[176:179], v[192:195], v[116:119]
	v_mfma_f32_16x16x32_bf16 v[104:107], v[168:171], v[200:203], v[104:107]
	v_mfma_f32_16x16x32_bf16 v[100:103], v[176:179], v[200:203], v[100:103]
	v_mfma_f32_16x16x32_bf16 v[88:91], v[168:171], v[208:211], v[88:91]
	v_mfma_f32_16x16x32_bf16 v[84:87], v[176:179], v[208:211], v[84:87]
	s_barrier
	s_add_u32 s2, s70, s0
	s_mov_b32 m0, s43
	v_lshl_add_u64 v[228:229], s[70:71], 0, v[136:137]
	s_addc_u32 s3, s71, s1
	ds_read_b128 v[212:215], v161
	ds_read_b128 v[216:219], v161 offset:1024
	ds_read_b128 v[220:223], v161 offset:2048
	ds_read_b128 v[224:227], v161 offset:3072
	global_load_lds_dwordx4 v[228:229], off
	v_lshl_add_u64 v[230:231], s[2:3], 0, v[136:137]
	s_mov_b32 m0, s44
	s_nop 0
	global_load_lds_dwordx4 v[230:231], off
	s_barrier
	s_waitcnt lgkmcnt(0)
	s_waitcnt lgkmcnt(0)
	v_mfma_f32_16x16x32_bf16 v[112:115], v[212:215], v[180:183], v[112:115]
	v_mfma_f32_16x16x32_bf16 v[108:111], v[220:223], v[180:183], v[108:111]
	s_cmp_lt_u32 s68, s36
	s_cselect_b64 vcc, -1, 0
	v_mfma_f32_16x16x32_bf16 v[96:99], v[212:215], v[188:191], v[96:99]
	s_and_b64 s[70:71], vcc, exec
	s_cselect_b32 s70, s38, s37
	v_mfma_f32_16x16x32_bf16 v[92:95], v[220:223], v[188:191], v[92:95]
	s_sub_i32 s69, s68, s36
	s_min_u32 s94, s68, s69
	v_mfma_f32_16x16x32_bf16 v[80:83], v[212:215], v[196:199], v[80:83]
	s_and_b64 s[72:73], vcc, exec
	s_cselect_b32 s69, s64, s66
	v_mfma_f32_16x16x32_bf16 v[76:79], v[220:223], v[196:199], v[76:79]
	s_cselect_b32 s71, s52, s65
	s_lshl_b64 s[72:73], s[94:95], 7
	v_mfma_f32_16x16x32_bf16 v[72:75], v[212:215], v[204:207], v[72:75]
	v_cndmask_b32_e32 v2, v138, v0, vcc
	s_add_u32 s72, s71, s72
	v_mfma_f32_16x16x32_bf16 v[68:71], v[220:223], v[204:207], v[68:71]
	s_mov_b32 s71, s95
	v_mfma_f32_16x16x32_bf16 v[112:115], v[216:219], v[184:187], v[112:115]
	s_addc_u32 s73, s69, s73
	v_mfma_f32_16x16x32_bf16 v[108:111], v[224:227], v[184:187], v[108:111]
	v_lshlrev_b64 v[232:233], 1, v[2:3]
	v_mfma_f32_16x16x32_bf16 v[96:99], v[216:219], v[192:195], v[96:99]
	s_lshl_b64 s[70:71], s[70:71], 7
	v_mfma_f32_16x16x32_bf16 v[92:95], v[224:227], v[192:195], v[92:95]
	v_lshl_add_u64 v[234:235], s[72:73], 0, v[232:233]
	v_mfma_f32_16x16x32_bf16 v[80:83], v[216:219], v[200:203], v[80:83]
	s_add_u32 s72, s72, s70
	v_mfma_f32_16x16x32_bf16 v[76:79], v[224:227], v[200:203], v[76:79]
	s_mov_b32 m0, s42
	v_mfma_f32_16x16x32_bf16 v[72:75], v[216:219], v[208:211], v[72:75]
	s_addc_u32 s73, s73, s71
	v_mfma_f32_16x16x32_bf16 v[68:71], v[224:227], v[208:211], v[68:71]
	s_barrier
	ds_read_b128 v[180:183], v144 offset:16384
	ds_read_b128 v[184:187], v144 offset:17408
	ds_read_b128 v[188:191], v145 offset:16384
	ds_read_b128 v[192:195], v145 offset:17408
	ds_read_b128 v[196:199], v159 offset:16384
	ds_read_b128 v[200:203], v159 offset:17408
	ds_read_b128 v[204:207], v160 offset:16384
	ds_read_b128 v[208:211], v160 offset:17408
	global_load_lds_dwordx4 v[234:235], off
	v_lshl_add_u64 v[234:235], s[72:73], 0, v[232:233]
	s_mov_b32 m0, s39
	s_nop 0
	global_load_lds_dwordx4 v[234:235], off
	s_barrier
; #define LDA(dst, b, h) for (int m = 0; m < 4; ++m) for (int k = 0; k < 2; ++k) \
;     dst[m][k] = *reinterpret_cast<const bf16x8*>(SA(b, h) + lds_byte(wr * 64 + m * 16 + fr, k * 32 + fq * 8))
; #define LDB(dst, b, h) for (int n = 0; n < 2; ++n) for (int k = 0; k < 2; ++k) \
;     dst[n][k] = *reinterpret_cast<const bf16x8*>(SB(b, h) + lds_byte(wc * 32 + n * 16 + fr, k * 32 + fq * 8))
; #define MMA(ai, bj, At_, Bt_) do { __builtin_amdgcn_s_setprio(1); \
;     for (int m = 0; m < 4; ++m) for (int n = 0; n < 2; ++n) for (int k = 0; k < 2; ++k) \
;       acc[ai][bj][m][n] = __builtin_amdgcn_mfma_f32_16x16x32_bf16(Bt_[n][k], At_[m][k], acc[ai][bj][m][n], 0, 0, 0); \
;     __builtin_amdgcn_s_setprio(0); } while (0)
; #define WAIT_V(n) asm volatile("s_waitcnt vmcnt(" #n ")" ::: "memory")
; #define WAIT_L(n) asm volatile("s_waitcnt lgkmcnt(" #n ")" ::: "memory")
; #define BAR __builtin_amdgcn_s_barrier()
; #define SCHED __builtin_amdgcn_sched_barrier(0)
; #define STG(P, PTR, LD, O0) do { const bf16_t* _g = (PTR); \
;     __builtin_amdgcn_global_load_lds((const unsigned*)(_g + O0), (lds_u32*)((P) + swave * 1024), 16, 0, 0); \
;     __builtin_amdgcn_global_load_lds((const unsigned*)(_g + (size_t)64 * (LD) + O0), (lds_u32*)((P) + swave * 1024 + 8192), 16, 0, 0); } while (0)
; #define LDA(dst, b, h) for (int m = 0; m < 4; ++m) for (int k = 0; k < 2; ++k) \
;     dst[m][k] = *reinterpret_cast<const bf16x8*>(SA(b, h) + lds_byte(wr * 64 + m * 16 + fr, k * 32 + fq * 8))
; #define LDB(dst, b, h) for (int n = 0; n < 2; ++n) for (int k = 0; k < 2; ++k) \
;     dst[n][k] = *reinterpret_cast<const bf16x8*>(SB(b, h) + lds_byte(wc * 32 + n * 16 + fr, k * 32 + fq * 8))
; #define WAIT_V(n) asm volatile("s_waitcnt vmcnt(" #n ")" ::: "memory")
; #define WAIT_L(n) asm volatile("s_waitcnt lgkmcnt(" #n ")" ::: "memory")
; #define BAR __builtin_amdgcn_s_barrier()
; #define SCHED __builtin_amdgcn_sched_barrier(0)
; __device__ __forceinline__ void gemm_stream(int swave, const GemmJob& J, char* shm, int vb, int G) {
;     ...
;       BAR; WAIT_L(0); MMA(1, 0, At, B0); BAR; SCHED;
;       STG(SB(0, 1), b2 + hB, ldb, offB0);
;       WAIT_V(6); BAR; MMA(1, 1, At, B1); BAR;
;       LDB(B0, 1, 0); SCHED; LDA(At, 1, 0); STGA(SA(0, 1), xA, xA1, k2, 1);
;       WAIT_L(8); BAR; WAIT_L(0); MMA(0, 0, At, B0); BAR; SCHED;
;       LDB(B1, 1, 1); STG(SB(1, 0), b3, ldb, offB0);
	s_waitcnt lgkmcnt(0)
	s_waitcnt lgkmcnt(0)
	v_mfma_f32_16x16x32_bf16 v[64:67], v[164:167], v[180:183], v[64:67]
	v_mfma_f32_16x16x32_bf16 v[60:63], v[172:175], v[180:183], v[60:63]
	v_mfma_f32_16x16x32_bf16 v[56:59], v[164:167], v[188:191], v[56:59]
	v_mfma_f32_16x16x32_bf16 v[52:55], v[172:175], v[188:191], v[52:55]
	v_mfma_f32_16x16x32_bf16 v[40:43], v[164:167], v[196:199], v[40:43]
	v_mfma_f32_16x16x32_bf16 v[36:39], v[172:175], v[196:199], v[36:39]
	v_mfma_f32_16x16x32_bf16 v[24:27], v[164:167], v[204:207], v[24:27]
	v_mfma_f32_16x16x32_bf16 v[20:23], v[172:175], v[204:207], v[20:23]
	v_mfma_f32_16x16x32_bf16 v[64:67], v[168:171], v[184:187], v[64:67]
	v_mfma_f32_16x16x32_bf16 v[60:63], v[176:179], v[184:187], v[60:63]
	v_mfma_f32_16x16x32_bf16 v[56:59], v[168:171], v[192:195], v[56:59]
	v_mfma_f32_16x16x32_bf16 v[52:55], v[176:179], v[192:195], v[52:55]
	v_mfma_f32_16x16x32_bf16 v[40:43], v[168:171], v[200:203], v[40:43]
	v_mfma_f32_16x16x32_bf16 v[36:39], v[176:179], v[200:203], v[36:39]
	v_mfma_f32_16x16x32_bf16 v[24:27], v[168:171], v[208:211], v[24:27]
	v_mfma_f32_16x16x32_bf16 v[20:23], v[176:179], v[208:211], v[20:23]
	s_barrier
	s_add_u32 s2, s2, s0
	s_addc_u32 s3, s3, s1
	v_lshl_add_u64 v[234:235], s[2:3], 0, v[136:137]
	s_add_u32 s2, s2, s0
	s_mov_b32 m0, s45
	s_addc_u32 s3, s3, s1
	global_load_lds_dwordx4 v[234:235], off
	v_lshl_add_u64 v[236:237], s[2:3], 0, v[136:137]
	s_mov_b32 m0, s46
	s_nop 0
	global_load_lds_dwordx4 v[236:237], off
	s_waitcnt vmcnt(6)
	s_barrier
	v_mfma_f32_16x16x32_bf16 v[48:51], v[212:215], v[180:183], v[48:51]
	v_mfma_f32_16x16x32_bf16 v[44:47], v[220:223], v[180:183], v[44:47]
	v_mfma_f32_16x16x32_bf16 v[32:35], v[212:215], v[188:191], v[32:35]
	v_mfma_f32_16x16x32_bf16 v[28:31], v[220:223], v[188:191], v[28:31]
	v_mfma_f32_16x16x32_bf16 v[16:19], v[212:215], v[196:199], v[16:19]
	v_mfma_f32_16x16x32_bf16 v[12:15], v[220:223], v[196:199], v[12:15]
	v_mfma_f32_16x16x32_bf16 v[8:11], v[212:215], v[204:207], v[8:11]
	v_mfma_f32_16x16x32_bf16 v[4:7], v[220:223], v[204:207], v[4:7]
	v_mfma_f32_16x16x32_bf16 v[48:51], v[216:219], v[184:187], v[48:51]
	v_mfma_f32_16x16x32_bf16 v[44:47], v[224:227], v[184:187], v[44:47]
	v_mfma_f32_16x16x32_bf16 v[32:35], v[216:219], v[192:195], v[32:35]
	v_mfma_f32_16x16x32_bf16 v[28:31], v[224:227], v[192:195], v[28:31]
	v_mfma_f32_16x16x32_bf16 v[16:19], v[216:219], v[200:203], v[16:19]
	v_mfma_f32_16x16x32_bf16 v[12:15], v[224:227], v[200:203], v[12:15]
	v_mfma_f32_16x16x32_bf16 v[8:11], v[216:219], v[208:211], v[8:11]
	v_mfma_f32_16x16x32_bf16 v[4:7], v[224:227], v[208:211], v[4:7]
	s_barrier
	ds_read_b128 v[164:167], v162
	ds_read_b128 v[168:171], v162 offset:1024
	ds_read_b128 v[172:175], v162 offset:2048
	ds_read_b128 v[176:179], v162 offset:3072
	s_add_u32 s2, s72, s70
	s_addc_u32 s3, s73, s71
	v_lshl_add_u64 v[212:213], s[2:3], 0, v[232:233]
	s_add_u32 s2, s2, s70
	s_mov_b32 m0, s47
	s_addc_u32 s3, s3, s71
	ds_read_b128 v[180:183], v144 offset:32768
	ds_read_b128 v[184:187], v144 offset:33792
	ds_read_b128 v[188:191], v145 offset:32768
	ds_read_b128 v[192:195], v145 offset:33792
	ds_read_b128 v[196:199], v159 offset:32768
	ds_read_b128 v[200:203], v159 offset:33792
	ds_read_b128 v[204:207], v160 offset:32768
	ds_read_b128 v[208:211], v160 offset:33792
	global_load_lds_dwordx4 v[212:213], off
	v_lshl_add_u64 v[212:213], s[2:3], 0, v[232:233]
	s_mov_b32 m0, s48
	s_nop 0
	global_load_lds_dwordx4 v[212:213], off
	s_waitcnt lgkmcnt(8)
	s_barrier
	s_waitcnt lgkmcnt(0)
	s_waitcnt lgkmcnt(0)
	v_mfma_f32_16x16x32_bf16 v[128:131], v[164:167], v[180:183], v[128:131]
	v_mfma_f32_16x16x32_bf16 v[124:127], v[172:175], v[180:183], v[124:127]
	v_mfma_f32_16x16x32_bf16 v[120:123], v[164:167], v[188:191], v[120:123]
	v_mfma_f32_16x16x32_bf16 v[116:119], v[172:175], v[188:191], v[116:119]
	v_mfma_f32_16x16x32_bf16 v[104:107], v[164:167], v[196:199], v[104:107]
	v_mfma_f32_16x16x32_bf16 v[100:103], v[172:175], v[196:199], v[100:103]
	v_mfma_f32_16x16x32_bf16 v[88:91], v[164:167], v[204:207], v[88:91]
	v_mfma_f32_16x16x32_bf16 v[84:87], v[172:175], v[204:207], v[84:87]
	v_mfma_f32_16x16x32_bf16 v[128:131], v[168:171], v[184:187], v[128:131]
	v_mfma_f32_16x16x32_bf16 v[124:127], v[176:179], v[184:187], v[124:127]
	v_mfma_f32_16x16x32_bf16 v[120:123], v[168:171], v[192:195], v[120:123]
	v_mfma_f32_16x16x32_bf16 v[116:119], v[176:179], v[192:195], v[116:119]
	v_mfma_f32_16x16x32_bf16 v[104:107], v[168:171], v[200:203], v[104:107]
	v_mfma_f32_16x16x32_bf16 v[100:103], v[176:179], v[200:203], v[100:103]
	v_mfma_f32_16x16x32_bf16 v[88:91], v[168:171], v[208:211], v[88:91]
	v_mfma_f32_16x16x32_bf16 v[84:87], v[176:179], v[208:211], v[84:87]
	s_barrier
	v_lshl_add_u64 v[228:229], v[228:229], 0, s[22:23]
	s_add_i32 m0, s42, 0x18000
	ds_read_b128 v[212:215], v163
	ds_read_b128 v[216:219], v163 offset:1024
	ds_read_b128 v[220:223], v163 offset:2048
	ds_read_b128 v[224:227], v163 offset:3072
	global_load_lds_dwordx4 v[228:229], off
	v_lshl_add_u64 v[228:229], v[230:231], 0, s[22:23]
	s_add_i32 m0, s42, 0x1a000
	s_nop 0
	global_load_lds_dwordx4 v[228:229], off
	s_barrier
; #define LDA(dst, b, h) for (int m = 0; m < 4; ++m) for (int k = 0; k < 2; ++k) \
;     dst[m][k] = *reinterpret_cast<const bf16x8*>(SA(b, h) + lds_byte(wr * 64 + m * 16 + fr, k * 32 + fq * 8))
; #define LDB(dst, b, h) for (int n = 0; n < 2; ++n) for (int k = 0; k < 2; ++k) \
;     dst[n][k] = *reinterpret_cast<const bf16x8*>(SB(b, h) + lds_byte(wc * 32 + n * 16 + fr, k * 32 + fq * 8))
; #define MMA(ai, bj, At_, Bt_) do { __builtin_amdgcn_s_setprio(1); \
;     for (int m = 0; m < 4; ++m) for (int n = 0; n < 2; ++n) for (int k = 0; k < 2; ++k) \
;       acc[ai][bj][m][n] = __builtin_amdgcn_mfma_f32_16x16x32_bf16(Bt_[n][k], At_[m][k], acc[ai][bj][m][n], 0, 0, 0); \
;     __builtin_amdgcn_s_setprio(0); } while (0)
; #define WAIT_V(n) asm volatile("s_waitcnt vmcnt(" #n ")" ::: "memory")
; #define WAIT_L(n) asm volatile("s_waitcnt lgkmcnt(" #n ")" ::: "memory")
; #define BAR __builtin_amdgcn_s_barrier()
; #define SCHED __builtin_amdgcn_sched_barrier(0)
; #define STG(P, PTR, LD, O0) do { const bf16_t* _g = (PTR); \
;     __builtin_amdgcn_global_load_lds((const unsigned*)(_g + O0), (lds_u32*)((P) + swave * 1024), 16, 0, 0); \
;     __builtin_amdgcn_global_load_lds((const unsigned*)(_g + (size_t)64 * (LD) + O0), (lds_u32*)((P) + swave * 1024 + 8192), 16, 0, 0); } while (0)
; #define LDA(dst, b, h) for (int m = 0; m < 4; ++m) for (int k = 0; k < 2; ++k) \
;     dst[m][k] = *reinterpret_cast<const bf16x8*>(SA(b, h) + lds_byte(wr * 64 + m * 16 + fr, k * 32 + fq * 8))
; #define LDB(dst, b, h) for (int n = 0; n < 2; ++n) for (int k = 0; k < 2; ++k) \
;     dst[n][k] = *reinterpret_cast<const bf16x8*>(SB(b, h) + lds_byte(wc * 32 + n * 16 + fr, k * 32 + fq * 8))
; #define WAIT_V(n) asm volatile("s_waitcnt vmcnt(" #n ")" ::: "memory")
; #define WAIT_L(n) asm volatile("s_waitcnt lgkmcnt(" #n ")" ::: "memory")
; #define BAR __builtin_amdgcn_s_barrier()
; #define SCHED __builtin_amdgcn_sched_barrier(0)
; __device__ __forceinline__ void gemm_stream(int swave, const GemmJob& J, char* shm, int vb, int G) {
;     ...
;       WAIT_L(8); BAR; WAIT_L(0); MMA(0, 0, At, B0); BAR; SCHED;
;       LDB(B1, 1, 1); STG(SB(1, 0), b3, ldb, offB0);
;       BAR; WAIT_L(0); MMA(0, 1, At, B1); BAR;
;       LDA(At, 1, 1); STGA(SA(1, 0), xA, xA1, k2 + 1, 0);
;       BAR; WAIT_L(0); MMA(1, 0, At, B0); BAR; SCHED;
;       STG(SB(1, 1), b3 + hB, ldb, offB0);
;       WAIT_V(6); BAR; MMA(1, 1, At, B1); BAR;
	s_waitcnt lgkmcnt(0)
	s_waitcnt lgkmcnt(0)
	v_mfma_f32_16x16x32_bf16 v[112:115], v[212:215], v[180:183], v[112:115]
	v_mfma_f32_16x16x32_bf16 v[108:111], v[220:223], v[180:183], v[108:111]
	s_or_b32 s68, s68, 1
	s_cmp_lt_u32 s68, s36
	v_mfma_f32_16x16x32_bf16 v[96:99], v[212:215], v[188:191], v[96:99]
	s_cselect_b64 vcc, -1, 0
	s_and_b64 s[2:3], vcc, exec
	v_mfma_f32_16x16x32_bf16 v[92:95], v[220:223], v[188:191], v[92:95]
	s_cselect_b32 s69, s38, s37
	s_sub_i32 s2, s68, s36
	v_mfma_f32_16x16x32_bf16 v[80:83], v[212:215], v[196:199], v[80:83]
	s_min_u32 s94, s68, s2
	s_and_b64 s[2:3], vcc, exec
	v_mfma_f32_16x16x32_bf16 v[76:79], v[220:223], v[196:199], v[76:79]
	s_cselect_b32 s64, s64, s66
	s_cselect_b32 s52, s52, s65
	v_mfma_f32_16x16x32_bf16 v[72:75], v[212:215], v[204:207], v[72:75]
	s_lshl_b64 s[2:3], s[94:95], 7
	v_cndmask_b32_e32 v2, v138, v0, vcc
	v_mfma_f32_16x16x32_bf16 v[68:71], v[220:223], v[204:207], v[68:71]
	s_add_u32 s2, s52, s2
	v_mfma_f32_16x16x32_bf16 v[112:115], v[216:219], v[184:187], v[112:115]
	s_addc_u32 s3, s64, s3
	v_mfma_f32_16x16x32_bf16 v[108:111], v[224:227], v[184:187], v[108:111]
	v_lshlrev_b64 v[228:229], 1, v[2:3]
	v_mfma_f32_16x16x32_bf16 v[96:99], v[216:219], v[192:195], v[96:99]
	s_lshl_b32 s52, s69, 7
	v_mfma_f32_16x16x32_bf16 v[92:95], v[224:227], v[192:195], v[92:95]
	v_lshl_add_u64 v[230:231], s[2:3], 0, v[228:229]
	v_mfma_f32_16x16x32_bf16 v[80:83], v[216:219], v[200:203], v[80:83]
	s_add_u32 s2, s2, s52
	v_mfma_f32_16x16x32_bf16 v[76:79], v[224:227], v[200:203], v[76:79]
	s_mov_b32 m0, s54
	v_mfma_f32_16x16x32_bf16 v[72:75], v[216:219], v[208:211], v[72:75]
	s_addc_u32 s3, s3, 0
	v_mfma_f32_16x16x32_bf16 v[68:71], v[224:227], v[208:211], v[68:71]
	s_barrier
	ds_read_b128 v[180:183], v144 offset:49152
	ds_read_b128 v[184:187], v144 offset:50176
	ds_read_b128 v[188:191], v145 offset:49152
	ds_read_b128 v[192:195], v145 offset:50176
	ds_read_b128 v[196:199], v159 offset:49152
	ds_read_b128 v[200:203], v159 offset:50176
	ds_read_b128 v[204:207], v160 offset:49152
	ds_read_b128 v[208:211], v160 offset:50176
	global_load_lds_dwordx4 v[230:231], off
	v_lshl_add_u64 v[228:229], s[2:3], 0, v[228:229]
	s_mov_b32 m0, s55
	s_nop 0
	global_load_lds_dwordx4 v[228:229], off
	s_barrier
	s_waitcnt lgkmcnt(0)
	s_waitcnt lgkmcnt(0)
	v_mfma_f32_16x16x32_bf16 v[64:67], v[164:167], v[180:183], v[64:67]
	v_mfma_f32_16x16x32_bf16 v[60:63], v[172:175], v[180:183], v[60:63]
	v_mfma_f32_16x16x32_bf16 v[56:59], v[164:167], v[188:191], v[56:59]
	v_mfma_f32_16x16x32_bf16 v[52:55], v[172:175], v[188:191], v[52:55]
	v_mfma_f32_16x16x32_bf16 v[40:43], v[164:167], v[196:199], v[40:43]
	v_mfma_f32_16x16x32_bf16 v[36:39], v[172:175], v[196:199], v[36:39]
	v_mfma_f32_16x16x32_bf16 v[24:27], v[164:167], v[204:207], v[24:27]
	v_mfma_f32_16x16x32_bf16 v[20:23], v[172:175], v[204:207], v[20:23]
	v_mfma_f32_16x16x32_bf16 v[64:67], v[168:171], v[184:187], v[64:67]
	v_mfma_f32_16x16x32_bf16 v[60:63], v[176:179], v[184:187], v[60:63]
	v_mfma_f32_16x16x32_bf16 v[56:59], v[168:171], v[192:195], v[56:59]
	v_mfma_f32_16x16x32_bf16 v[52:55], v[176:179], v[192:195], v[52:55]
	v_mfma_f32_16x16x32_bf16 v[40:43], v[168:171], v[200:203], v[40:43]
	v_mfma_f32_16x16x32_bf16 v[36:39], v[176:179], v[200:203], v[36:39]
	v_mfma_f32_16x16x32_bf16 v[24:27], v[168:171], v[208:211], v[24:27]
	v_mfma_f32_16x16x32_bf16 v[20:23], v[176:179], v[208:211], v[20:23]
	s_barrier
	v_lshl_add_u64 v[164:165], v[234:235], 0, s[22:23]
	s_add_i32 m0, s42, 0x1c000
	s_nop 0
	global_load_lds_dwordx4 v[164:165], off
	v_lshl_add_u64 v[164:165], v[236:237], 0, s[22:23]
	s_add_i32 m0, s42, 0x1e000
	s_nop 0
	global_load_lds_dwordx4 v[164:165], off
	s_waitcnt vmcnt(6)
	s_barrier
	v_mfma_f32_16x16x32_bf16 v[48:51], v[212:215], v[180:183], v[48:51]
	v_mfma_f32_16x16x32_bf16 v[44:47], v[220:223], v[180:183], v[44:47]
	s_add_i32 s29, s29, 2
	v_mfma_f32_16x16x32_bf16 v[32:35], v[212:215], v[188:191], v[32:35]
	s_add_u32 s20, s20, 0x100
	v_mfma_f32_16x16x32_bf16 v[28:31], v[220:223], v[188:191], v[28:31]
	s_addc_u32 s21, s21, 0
	v_mfma_f32_16x16x32_bf16 v[16:19], v[212:215], v[196:199], v[16:19]
	s_cmp_ge_u32 s33, s49
	v_mfma_f32_16x16x32_bf16 v[12:15], v[220:223], v[196:199], v[12:15]
	s_mov_b32 s2, s33
	v_mfma_f32_16x16x32_bf16 v[8:11], v[212:215], v[204:207], v[8:11]
	v_mfma_f32_16x16x32_bf16 v[4:7], v[220:223], v[204:207], v[4:7]
	v_mfma_f32_16x16x32_bf16 v[48:51], v[216:219], v[184:187], v[48:51]
	v_mfma_f32_16x16x32_bf16 v[44:47], v[224:227], v[184:187], v[44:47]
	v_mfma_f32_16x16x32_bf16 v[32:35], v[216:219], v[192:195], v[32:35]
	v_mfma_f32_16x16x32_bf16 v[28:31], v[224:227], v[192:195], v[28:31]
	v_mfma_f32_16x16x32_bf16 v[16:19], v[216:219], v[200:203], v[16:19]
	v_mfma_f32_16x16x32_bf16 v[12:15], v[224:227], v[200:203], v[12:15]
	v_mfma_f32_16x16x32_bf16 v[8:11], v[216:219], v[208:211], v[8:11]
	v_mfma_f32_16x16x32_bf16 v[4:7], v[224:227], v[208:211], v[4:7]
	s_barrier
; __device__ __forceinline__ unsigned pk2(float lo, float hi) { f32x2_t v = {lo, hi}; bf16x2_t b = __builtin_convertvector(v, bf16x2_t); return __builtin_bit_cast(unsigned, b); }
; __device__ __forceinline__ void gemm_stream(int swave, const GemmJob& J, char* shm, int vb, int G) {
;     ...
;       bf16_t* C = (bf16_t*)((char*)J.c0 + (size_t)cg * J.strideC);
; #pragma unroll
;       for (int ai = 0; ai < 2; ++ai)
; #pragma unroll
;         for (int m = 0; m < 4; ++m)
; #pragma unroll
;           for (int bj = 0; bj < 2; ++bj) {
;             const f32x4 v0 = acc[ai][bj][m][0], v1 = acc[ai][bj][m][1];
;             uint4 o; o.x = pk2(v0[0], v0[1]); o.y = pk2(v0[2], v0[3]); o.z = pk2(v1[0], v1[1]); o.w = pk2(v1[2], v1[3]);
;             *(uint4*)(C + (size_t)(cbrow + ai * 128 + wr * 64 + m * 16 + fr) * J.ldc + cbcol + bj * 128 + wc * 32 + fq * 8) = o;
;           }
;     }
;     if (!has_next) break;
	s_cbranch_scc0 .LBB0_729
	v_add_u32_e32 v164, s5, v1
	s_ashr_i32 s5, s4, 31
	s_lshl_b64 s[2:3], s[4:5], 1
	v_ashrrev_i32_e32 v2, 31, v164
	s_add_u32 s2, s50, s2
	v_cvt_pk_bf16_f32 v128, v128, v129
	v_cvt_pk_bf16_f32 v129, v130, v131
	v_cvt_pk_bf16_f32 v130, v124, v125
	v_mul_lo_u32 v2, v2, s18
	v_mad_u64_u32 v[124:125], s[4:5], v164, s18, 0
	s_addc_u32 s3, s51, s3
	v_add_u32_e32 v125, v125, v2
	v_lshl_add_u64 v[124:125], v[124:125], 1, s[2:3]
	v_mov_b32_e32 v141, v3
	v_lshl_add_u64 v[124:125], v[124:125], 0, v[140:141]
	v_mov_b32_e32 v143, v3
	v_lshl_add_u64 v[124:125], v[124:125], 0, v[142:143]
	s_lshl_b32 s2, s18, 5
	s_mov_b32 s3, 0
	s_mul_i32 s4, s18, 0xa0
	s_mov_b32 s5, 0
	v_cvt_pk_bf16_f32 v112, v112, v113
	v_cvt_pk_bf16_f32 v113, v114, v115
	v_cvt_pk_bf16_f32 v114, v108, v109
	v_cvt_pk_bf16_f32 v115, v110, v111
	global_store_dwordx4 v[124:125], v[112:115], off offset:256
	v_cvt_pk_bf16_f32 v131, v126, v127
	v_cvt_pk_bf16_f32 v96, v96, v97
	v_lshl_add_u64 v[112:113], v[124:125], 0, s[2:3]
	v_cvt_pk_bf16_f32 v97, v98, v99
	v_cvt_pk_bf16_f32 v98, v92, v93
	v_cvt_pk_bf16_f32 v99, v94, v95
	global_store_dwordx4 v[124:125], v[128:131], off
	global_store_dwordx4 v[112:113], v[96:99], off offset:256
	v_cvt_pk_bf16_f32 v108, v120, v121
	v_cvt_pk_bf16_f32 v109, v122, v123
	v_lshl_add_u64 v[96:97], v[112:113], 0, s[2:3]
	v_cvt_pk_bf16_f32 v110, v116, v117
	v_cvt_pk_bf16_f32 v111, v118, v119
	v_cvt_pk_bf16_f32 v80, v80, v81
	v_cvt_pk_bf16_f32 v81, v82, v83
	v_cvt_pk_bf16_f32 v82, v76, v77
	v_cvt_pk_bf16_f32 v83, v78, v79
	global_store_dwordx4 v[112:113], v[108:111], off
	global_store_dwordx4 v[96:97], v[80:83], off offset:256
	v_cvt_pk_bf16_f32 v64, v64, v65
	v_cvt_pk_bf16_f32 v65, v66, v67
	v_lshl_add_u64 v[80:81], v[96:97], 0, s[2:3]
	v_cvt_pk_bf16_f32 v66, v60, v61
	v_lshl_add_u64 v[60:61], v[80:81], 0, s[4:5]
	v_cvt_pk_bf16_f32 v72, v72, v73
	v_cvt_pk_bf16_f32 v73, v74, v75
	v_cvt_pk_bf16_f32 v74, v68, v69
	v_cvt_pk_bf16_f32 v67, v62, v63
	v_cvt_pk_bf16_f32 v92, v104, v105
	v_cvt_pk_bf16_f32 v93, v106, v107
	v_cvt_pk_bf16_f32 v94, v100, v101
	v_cvt_pk_bf16_f32 v95, v102, v103
	v_cvt_pk_bf16_f32 v76, v88, v89
	v_cvt_pk_bf16_f32 v77, v90, v91
	v_cvt_pk_bf16_f32 v78, v84, v85
	v_cvt_pk_bf16_f32 v79, v86, v87
	v_cvt_pk_bf16_f32 v75, v70, v71
	v_cvt_pk_bf16_f32 v48, v48, v49
	v_cvt_pk_bf16_f32 v49, v50, v51
	v_cvt_pk_bf16_f32 v50, v44, v45
	v_cvt_pk_bf16_f32 v51, v46, v47
	global_store_dwordx4 v[96:97], v[92:95], off
	global_store_dwordx4 v[80:81], v[76:79], off
	global_store_dwordx4 v[80:81], v[72:75], off offset:256
	global_store_dwordx4 v[60:61], v[48:51], off offset:256
	v_cvt_pk_bf16_f32 v32, v32, v33
	v_cvt_pk_bf16_f32 v33, v34, v35
	v_lshl_add_u64 v[48:49], v[60:61], 0, s[2:3]
	v_cvt_pk_bf16_f32 v34, v28, v29
	v_cvt_pk_bf16_f32 v35, v30, v31
	global_store_dwordx4 v[60:61], v[64:67], off
	global_store_dwordx4 v[48:49], v[32:35], off offset:256
	v_cvt_pk_bf16_f32 v44, v56, v57
	v_cvt_pk_bf16_f32 v45, v58, v59
	v_lshl_add_u64 v[32:33], v[48:49], 0, s[2:3]
	v_cvt_pk_bf16_f32 v46, v52, v53
	v_cvt_pk_bf16_f32 v47, v54, v55
	v_cvt_pk_bf16_f32 v16, v16, v17
	v_cvt_pk_bf16_f32 v17, v18, v19
	v_cvt_pk_bf16_f32 v18, v12, v13
	v_cvt_pk_bf16_f32 v19, v14, v15
	global_store_dwordx4 v[48:49], v[44:47], off
	global_store_dwordx4 v[32:33], v[16:19], off offset:256
	v_cvt_pk_bf16_f32 v28, v40, v41
	v_cvt_pk_bf16_f32 v29, v42, v43
	v_lshl_add_u64 v[16:17], v[32:33], 0, s[2:3]
	v_cvt_pk_bf16_f32 v30, v36, v37
	v_cvt_pk_bf16_f32 v31, v38, v39
	v_cvt_pk_bf16_f32 v12, v24, v25
	v_cvt_pk_bf16_f32 v13, v26, v27
	v_cvt_pk_bf16_f32 v14, v20, v21
	v_cvt_pk_bf16_f32 v15, v22, v23
	v_cvt_pk_bf16_f32 v8, v8, v9
	v_cvt_pk_bf16_f32 v9, v10, v11
	v_cvt_pk_bf16_f32 v10, v4, v5
	v_cvt_pk_bf16_f32 v11, v6, v7
	s_and_b64 vcc, exec, s[6:7]
	s_mov_b64 s[2:3], s[14:15]
	s_mov_b64 s[16:17], s[12:13]
	s_mov_b64 s[8:9], s[10:11]
	s_mov_b32 s4, s56
	s_mov_b32 s5, s28
	global_store_dwordx4 v[32:33], v[28:31], off
	global_store_dwordx4 v[16:17], v[12:15], off
	global_store_dwordx4 v[16:17], v[8:11], off offset:256
	s_cbranch_vccz .LBB0_726
	s_waitcnt vmcnt(0)
	s_movk_i32 s66, 0x100
	v_cmp_gt_u32_e32 vcc, s66, v135
	s_and_saveexec_b64 s[0:1], vcc
	s_cbranch_execz .LBB0_733
	s_barrier
